# PEER V loop: fp4 row gathers through structured buffer loads (index=expert id, stride 512), removing the 8 per-iteration address VALU ops
# speedup vs baseline: 1.0020x; 1.0020x over previous
; #define FP4_AXPY(k) { acc2[k] += w * __builtin_amdgcn_cvt_scalef32_pk_f32_fp4(vr[q].x, 1.0f, k); acc2[4 + k] += w * __builtin_amdgcn_cvt_scalef32_pk_f32_fp4(vr[q].y, 1.0f, k); \
;                       acc2[8 + k] += w * __builtin_amdgcn_cvt_scalef32_pk_f32_fp4(vr[q].z, 1.0f, k); acc2[12 + k] += w * __builtin_amdgcn_cvt_scalef32_pk_f32_fp4(vr[q].w, 1.0f, k); }
; __device__ __forceinline__ void peer_token(const Params& P, int t, int lane, int* sidx, float* sval, const int* sid, const float* sgate, const unsigned* szero) {
;     ...
;     const unsigned char* Vb = P.ws + WS_V;
;     const unsigned vlo = (unsigned)l5 * 16u;
; #pragma unroll 1
;     for (int e0 = 0; e0 < 128; e0 += 16) {
;         uint4 vr[8];
; #pragma unroll
;         for (int q = 0; q < 8; ++q) vr[q] = *(const uint4*)(Vb + ((unsigned)sid[e0 + 2 * q + half] * 512u + vlo));
;         const float* sw = (const float*)sidx + e0;
;         const f32x4 w0 = *(const f32x4*)(sw), w1 = *(const f32x4*)(sw + 4), w2 = *(const f32x4*)(sw + 8), w3 = *(const f32x4*)(sw + 12);
;         const float wq[16] = {w0[0], w0[1], w0[2], w0[3], w1[0], w1[1], w1[2], w1[3], w2[0], w2[1], w2[2], w2[3], w3[0], w3[1], w3[2], w3[3]};
; #pragma unroll
;         for (int q = 0; q < 8; ++q) {
;             const float w = half ? wq[2 * q + 1] : wq[2 * q];
;     ...
;             FP4_AXPY(0) FP4_AXPY(1) FP4_AXPY(2) FP4_AXPY(3)
.Lp5_v_head:
	s_mul_i32 s16, s85, s22
	v_add_u32_e32 v112, s16, v130
	v_cmp_gt_i32_e32 vcc, s20, v112
	s_and_saveexec_b64 s[16:17], vcc
	s_cbranch_execz .Lp5_v_next
	v_ashrrev_i32_e32 v113, 31, v112
	v_lshlrev_b64 v[0:1], 11, v[112:113]
	v_lshl_add_u64 v[110:111], s[36:37], 0, v[0:1]
	v_lshl_add_u32 v139, s85, 10, v114
	v_mov_b32_e32 v42, 0
	v_lshlrev_b64 v[40:41], 10, v[112:113]
	s_mov_b32 s18, -16
	v_add_u32_e32 v74, v139, v128
	s_mov_b32 s92, s14
	s_and_b32 s93, s15, 0xffff
	s_or_b32 s93, s93, 0x2000000
	s_mov_b32 s94, 0x100000
	s_mov_b32 s95, 0x20000
	v_mov_b32_e32 v87, v122
	v_mov_b32_e32 v89, v122
	v_mov_b32_e32 v91, v122
	v_mov_b32_e32 v7, v122
	v_mov_b32_e32 v43, v42
	v_mov_b32_e32 v68, v42
	v_mov_b32_e32 v69, v42
	v_mov_b32_e32 v66, v42
	v_mov_b32_e32 v67, v42
	v_mov_b32_e32 v70, v42
	v_mov_b32_e32 v71, v42
	v_mov_b32_e32 v72, v42
	v_mov_b32_e32 v73, v42
	v_mov_b32_e32 v58, v42
	v_mov_b32_e32 v59, v42
	v_mov_b32_e32 v60, v42
	v_mov_b32_e32 v61, v42
	v_mov_b32_e32 v62, v42
	v_mov_b32_e32 v63, v42
	v_mov_b32_e32 v64, v42
	v_mov_b32_e32 v65, v42
	v_mov_b32_e32 v50, v42
	v_mov_b32_e32 v51, v42
	v_mov_b32_e32 v52, v42
	v_mov_b32_e32 v53, v42
	v_mov_b32_e32 v54, v42
	v_mov_b32_e32 v55, v42
	v_mov_b32_e32 v56, v42
	v_mov_b32_e32 v57, v42
	v_mov_b32_e32 v44, v42
	v_mov_b32_e32 v45, v42
	v_mov_b32_e32 v46, v42
	v_mov_b32_e32 v47, v42
	v_mov_b32_e32 v48, v42
	v_mov_b32_e32 v49, v42
.LBB0_1424:
	ds_read_b32 v86, v74
	ds_read_b32 v88, v74 offset:8
	ds_read_b32 v90, v74 offset:16
	ds_read_b32 v6, v74 offset:24
	ds_read_b32 v80, v74 offset:512
	ds_read_b32 v82, v74 offset:520
	ds_read_b32 v28, v74 offset:528
	ds_read_b32 v30, v74 offset:536
	ds_read_b32 v16, v74 offset:544
	ds_read_b32 v18, v74 offset:552
	s_add_i32 s18, s18, 16
	s_waitcnt lgkmcnt(9)
	buffer_load_dwordx4 v[76:79], v[86:87], s[92:95], 0 idxen offen
	ds_read_b32 v86, v74 offset:32
	s_waitcnt lgkmcnt(9)
	buffer_load_dwordx4 v[36:39], v[88:89], s[92:95], 0 idxen offen
	ds_read_b32 v88, v74 offset:40
	s_waitcnt lgkmcnt(9)
	buffer_load_dwordx4 v[32:35], v[90:91], s[92:95], 0 idxen offen
	ds_read_b32 v90, v74 offset:48
	s_waitcnt lgkmcnt(9)
	buffer_load_dwordx4 v[24:27], v[6:7], s[92:95], 0 idxen offen
	ds_read_b32 v6, v74 offset:56
	s_waitcnt lgkmcnt(3)
	buffer_load_dwordx4 v[20:23], v[86:87], s[92:95], 0 idxen offen
	s_waitcnt lgkmcnt(2)
	buffer_load_dwordx4 v[12:15], v[88:89], s[92:95], 0 idxen offen
	s_waitcnt lgkmcnt(1)
	buffer_load_dwordx4 v[8:11], v[90:91], s[92:95], 0 idxen offen
	s_waitcnt lgkmcnt(0)
	buffer_load_dwordx4 v[0:3], v[6:7], s[92:95], 0 idxen offen
	ds_read_b32 v4, v74 offset:560
	ds_read_b32 v6, v74 offset:568
	v_add_u32_e32 v74, 64, v74
	s_waitcnt lgkmcnt(2)
	s_cmpk_lt_u32 s18, 0x70
	s_waitcnt vmcnt(7)
	v_cvt_scalef32_pk_f32_fp4 v[84:85], v76, 1.0
	v_pk_fma_f32 v[68:69], v[80:81], v[84:85], v[68:69] op_sel_hi:[0,1,1]
	v_cvt_scalef32_pk_f32_fp4 v[84:85], v77, 1.0
	v_pk_fma_f32 v[58:59], v[80:81], v[84:85], v[58:59] op_sel_hi:[0,1,1]
	v_cvt_scalef32_pk_f32_fp4 v[84:85], v78, 1.0
	v_pk_fma_f32 v[50:51], v[80:81], v[84:85], v[50:51] op_sel_hi:[0,1,1]
	v_cvt_scalef32_pk_f32_fp4 v[84:85], v79, 1.0
	v_pk_fma_f32 v[44:45], v[80:81], v[84:85], v[44:45] op_sel_hi:[0,1,1]
	v_cvt_scalef32_pk_f32_fp4 v[84:85], v76, 1.0 op_sel:[1,0,0]
	v_pk_fma_f32 v[66:67], v[80:81], v[84:85], v[66:67] op_sel_hi:[0,1,1]
	v_cvt_scalef32_pk_f32_fp4 v[84:85], v77, 1.0 op_sel:[1,0,0]
	v_pk_fma_f32 v[60:61], v[80:81], v[84:85], v[60:61] op_sel_hi:[0,1,1]
	v_cvt_scalef32_pk_f32_fp4 v[84:85], v78, 1.0 op_sel:[1,0,0]
	v_pk_fma_f32 v[52:53], v[80:81], v[84:85], v[52:53] op_sel_hi:[0,1,1]
	v_cvt_scalef32_pk_f32_fp4 v[84:85], v79, 1.0 op_sel:[1,0,0]
	v_pk_fma_f32 v[46:47], v[80:81], v[84:85], v[46:47] op_sel_hi:[0,1,1]
	v_cvt_scalef32_pk_f32_fp4 v[84:85], v76, 1.0 op_sel:[0,1,0]
	v_pk_fma_f32 v[70:71], v[80:81], v[84:85], v[70:71] op_sel_hi:[0,1,1]
	v_cvt_scalef32_pk_f32_fp4 v[84:85], v77, 1.0 op_sel:[0,1,0]
	v_pk_fma_f32 v[62:63], v[80:81], v[84:85], v[62:63] op_sel_hi:[0,1,1]
	v_cvt_scalef32_pk_f32_fp4 v[84:85], v78, 1.0 op_sel:[0,1,0]
	v_pk_fma_f32 v[54:55], v[80:81], v[84:85], v[54:55] op_sel_hi:[0,1,1]
	v_cvt_scalef32_pk_f32_fp4 v[84:85], v79, 1.0 op_sel:[0,1,0]
	v_pk_fma_f32 v[48:49], v[80:81], v[84:85], v[48:49] op_sel_hi:[0,1,1]
	v_cvt_scalef32_pk_f32_fp4 v[84:85], v76, 1.0 op_sel:[1,1,0]
	v_cvt_scalef32_pk_f32_fp4 v[76:77], v77, 1.0 op_sel:[1,1,0]
	v_pk_fma_f32 v[64:65], v[80:81], v[76:77], v[64:65] op_sel_hi:[0,1,1]
	v_cvt_scalef32_pk_f32_fp4 v[76:77], v78, 1.0 op_sel:[1,1,0]
	v_pk_fma_f32 v[56:57], v[80:81], v[76:77], v[56:57] op_sel_hi:[0,1,1]
	v_cvt_scalef32_pk_f32_fp4 v[76:77], v79, 1.0 op_sel:[1,1,0]
	v_pk_fma_f32 v[42:43], v[80:81], v[76:77], v[42:43] op_sel_hi:[0,1,1]
	s_waitcnt vmcnt(6)
; #define FP4_AXPY(k) { acc2[k] += w * __builtin_amdgcn_cvt_scalef32_pk_f32_fp4(vr[q].x, 1.0f, k); acc2[4 + k] += w * __builtin_amdgcn_cvt_scalef32_pk_f32_fp4(vr[q].y, 1.0f, k); \
;                       acc2[8 + k] += w * __builtin_amdgcn_cvt_scalef32_pk_f32_fp4(vr[q].z, 1.0f, k); acc2[12 + k] += w * __builtin_amdgcn_cvt_scalef32_pk_f32_fp4(vr[q].w, 1.0f, k); }
; __device__ __forceinline__ void peer_token(const Params& P, int t, int lane, int* sidx, float* sval, const int* sid, const float* sgate, const unsigned* szero) {
;     ...
;         for (int q = 0; q < 8; ++q) {
;             const float w = half ? wq[2 * q + 1] : wq[2 * q];
;     ...
;             FP4_AXPY(0) FP4_AXPY(1) FP4_AXPY(2) FP4_AXPY(3)
;     ...
;         }
	v_cvt_scalef32_pk_f32_fp4 v[78:79], v36, 1.0
	v_pk_fma_f32 v[68:69], v[82:83], v[78:79], v[68:69] op_sel_hi:[0,1,1]
	v_cvt_scalef32_pk_f32_fp4 v[78:79], v37, 1.0
	v_pk_fma_f32 v[58:59], v[82:83], v[78:79], v[58:59] op_sel_hi:[0,1,1]
	v_cvt_scalef32_pk_f32_fp4 v[78:79], v38, 1.0
	v_pk_fma_f32 v[50:51], v[82:83], v[78:79], v[50:51] op_sel_hi:[0,1,1]
	v_cvt_scalef32_pk_f32_fp4 v[78:79], v39, 1.0
	v_pk_fma_f32 v[44:45], v[82:83], v[78:79], v[44:45] op_sel_hi:[0,1,1]
	v_cvt_scalef32_pk_f32_fp4 v[78:79], v36, 1.0 op_sel:[1,0,0]
	v_pk_fma_f32 v[66:67], v[82:83], v[78:79], v[66:67] op_sel_hi:[0,1,1]
	v_cvt_scalef32_pk_f32_fp4 v[78:79], v37, 1.0 op_sel:[1,0,0]
	v_pk_fma_f32 v[60:61], v[82:83], v[78:79], v[60:61] op_sel_hi:[0,1,1]
	v_cvt_scalef32_pk_f32_fp4 v[78:79], v38, 1.0 op_sel:[1,0,0]
	v_pk_fma_f32 v[52:53], v[82:83], v[78:79], v[52:53] op_sel_hi:[0,1,1]
	v_cvt_scalef32_pk_f32_fp4 v[78:79], v39, 1.0 op_sel:[1,0,0]
	v_pk_fma_f32 v[46:47], v[82:83], v[78:79], v[46:47] op_sel_hi:[0,1,1]
	v_cvt_scalef32_pk_f32_fp4 v[78:79], v36, 1.0 op_sel:[0,1,0]
	v_pk_fma_f32 v[70:71], v[82:83], v[78:79], v[70:71] op_sel_hi:[0,1,1]
	v_cvt_scalef32_pk_f32_fp4 v[78:79], v37, 1.0 op_sel:[0,1,0]
	v_pk_fma_f32 v[62:63], v[82:83], v[78:79], v[62:63] op_sel_hi:[0,1,1]
	v_cvt_scalef32_pk_f32_fp4 v[78:79], v38, 1.0 op_sel:[0,1,0]
	v_pk_fma_f32 v[54:55], v[82:83], v[78:79], v[54:55] op_sel_hi:[0,1,1]
	v_cvt_scalef32_pk_f32_fp4 v[78:79], v39, 1.0 op_sel:[0,1,0]
	v_pk_fma_f32 v[48:49], v[82:83], v[78:79], v[48:49] op_sel_hi:[0,1,1]
	v_cvt_scalef32_pk_f32_fp4 v[78:79], v36, 1.0 op_sel:[1,1,0]
	v_cvt_scalef32_pk_f32_fp4 v[36:37], v37, 1.0 op_sel:[1,1,0]
	v_pk_fma_f32 v[36:37], v[82:83], v[36:37], v[64:65] op_sel_hi:[0,1,1]
	v_cvt_scalef32_pk_f32_fp4 v[64:65], v38, 1.0 op_sel:[1,1,0]
	v_pk_fma_f32 v[56:57], v[82:83], v[64:65], v[56:57] op_sel_hi:[0,1,1]
	s_waitcnt vmcnt(5)
	v_cvt_scalef32_pk_f32_fp4 v[64:65], v33, 1.0
	v_pk_fma_f32 v[58:59], v[28:29], v[64:65], v[58:59] op_sel_hi:[0,1,1]
	v_cvt_scalef32_pk_f32_fp4 v[64:65], v34, 1.0
	v_cvt_scalef32_pk_f32_fp4 v[38:39], v39, 1.0 op_sel:[1,1,0]
	v_pk_fma_f32 v[50:51], v[28:29], v[64:65], v[50:51] op_sel_hi:[0,1,1]
	v_cvt_scalef32_pk_f32_fp4 v[64:65], v35, 1.0
	v_pk_fma_f32 v[38:39], v[82:83], v[38:39], v[42:43] op_sel_hi:[0,1,1]
	v_cvt_scalef32_pk_f32_fp4 v[42:43], v32, 1.0
	v_pk_fma_f32 v[44:45], v[28:29], v[64:65], v[44:45] op_sel_hi:[0,1,1]
	v_cvt_scalef32_pk_f32_fp4 v[64:65], v32, 1.0 op_sel:[1,0,0]
	v_pk_fma_f32 v[42:43], v[28:29], v[42:43], v[68:69] op_sel_hi:[0,1,1]
	v_pk_fma_f32 v[64:65], v[28:29], v[64:65], v[66:67] op_sel_hi:[0,1,1]
	v_cvt_scalef32_pk_f32_fp4 v[66:67], v33, 1.0 op_sel:[1,0,0]
	v_cvt_scalef32_pk_f32_fp4 v[68:69], v33, 1.0 op_sel:[0,1,0]
	v_pk_fma_f32 v[60:61], v[28:29], v[66:67], v[60:61] op_sel_hi:[0,1,1]
	v_cvt_scalef32_pk_f32_fp4 v[66:67], v34, 1.0 op_sel:[1,0,0]
	v_pk_fma_f32 v[62:63], v[28:29], v[68:69], v[62:63] op_sel_hi:[0,1,1]
	v_cvt_scalef32_pk_f32_fp4 v[68:69], v34, 1.0 op_sel:[0,1,0]
	v_pk_fma_f32 v[52:53], v[28:29], v[66:67], v[52:53] op_sel_hi:[0,1,1]
	v_cvt_scalef32_pk_f32_fp4 v[66:67], v35, 1.0 op_sel:[1,0,0]
	v_pk_fma_f32 v[54:55], v[28:29], v[68:69], v[54:55] op_sel_hi:[0,1,1]
	v_cvt_scalef32_pk_f32_fp4 v[68:69], v35, 1.0 op_sel:[0,1,0]
	v_pk_fma_f32 v[46:47], v[28:29], v[66:67], v[46:47] op_sel_hi:[0,1,1]
	v_cvt_scalef32_pk_f32_fp4 v[66:67], v32, 1.0 op_sel:[0,1,0]
	v_pk_fma_f32 v[48:49], v[28:29], v[68:69], v[48:49] op_sel_hi:[0,1,1]
	v_cvt_scalef32_pk_f32_fp4 v[68:69], v32, 1.0 op_sel:[1,1,0]
	v_cvt_scalef32_pk_f32_fp4 v[32:33], v33, 1.0 op_sel:[1,1,0]
	v_pk_fma_f32 v[72:73], v[80:81], v[84:85], v[72:73] op_sel_hi:[0,1,1]
	v_pk_fma_f32 v[32:33], v[28:29], v[32:33], v[36:37] op_sel_hi:[0,1,1]
	v_cvt_scalef32_pk_f32_fp4 v[36:37], v34, 1.0 op_sel:[1,1,0]
	v_pk_fma_f32 v[72:73], v[82:83], v[78:79], v[72:73] op_sel_hi:[0,1,1]
	v_pk_fma_f32 v[36:37], v[28:29], v[36:37], v[56:57] op_sel_hi:[0,1,1]
	v_cvt_scalef32_pk_f32_fp4 v[34:35], v35, 1.0 op_sel:[1,1,0]
	s_waitcnt vmcnt(4)
	v_cvt_scalef32_pk_f32_fp4 v[56:57], v25, 1.0 op_sel:[1,0,0]
	v_pk_fma_f32 v[66:67], v[28:29], v[66:67], v[70:71] op_sel_hi:[0,1,1]
	v_pk_fma_f32 v[68:69], v[28:29], v[68:69], v[72:73] op_sel_hi:[0,1,1]
	v_pk_fma_f32 v[28:29], v[28:29], v[34:35], v[38:39] op_sel_hi:[0,1,1]
	v_cvt_scalef32_pk_f32_fp4 v[34:35], v24, 1.0
	v_cvt_scalef32_pk_f32_fp4 v[38:39], v25, 1.0
	v_pk_fma_f32 v[56:57], v[30:31], v[56:57], v[60:61] op_sel_hi:[0,1,1]
	v_cvt_scalef32_pk_f32_fp4 v[60:61], v25, 1.0 op_sel:[0,1,0]
	v_pk_fma_f32 v[34:35], v[30:31], v[34:35], v[42:43] op_sel_hi:[0,1,1]
	v_pk_fma_f32 v[38:39], v[30:31], v[38:39], v[58:59] op_sel_hi:[0,1,1]
	v_cvt_scalef32_pk_f32_fp4 v[42:43], v26, 1.0
	v_cvt_scalef32_pk_f32_fp4 v[58:59], v26, 1.0 op_sel:[1,0,0]
	v_pk_fma_f32 v[60:61], v[30:31], v[60:61], v[62:63] op_sel_hi:[0,1,1]
	v_cvt_scalef32_pk_f32_fp4 v[62:63], v26, 1.0 op_sel:[0,1,0]
	v_pk_fma_f32 v[42:43], v[30:31], v[42:43], v[50:51] op_sel_hi:[0,1,1]
	v_cvt_scalef32_pk_f32_fp4 v[50:51], v27, 1.0
	v_pk_fma_f32 v[52:53], v[30:31], v[58:59], v[52:53] op_sel_hi:[0,1,1]
	v_cvt_scalef32_pk_f32_fp4 v[58:59], v27, 1.0 op_sel:[1,0,0]
	v_pk_fma_f32 v[54:55], v[30:31], v[62:63], v[54:55] op_sel_hi:[0,1,1]
	v_cvt_scalef32_pk_f32_fp4 v[62:63], v27, 1.0 op_sel:[0,1,0]
	v_pk_fma_f32 v[44:45], v[30:31], v[50:51], v[44:45] op_sel_hi:[0,1,1]
	v_cvt_scalef32_pk_f32_fp4 v[50:51], v24, 1.0 op_sel:[1,0,0]
	v_pk_fma_f32 v[46:47], v[30:31], v[58:59], v[46:47] op_sel_hi:[0,1,1]
	v_cvt_scalef32_pk_f32_fp4 v[58:59], v24, 1.0 op_sel:[0,1,0]
	v_pk_fma_f32 v[48:49], v[30:31], v[62:63], v[48:49] op_sel_hi:[0,1,1]
	v_cvt_scalef32_pk_f32_fp4 v[62:63], v24, 1.0 op_sel:[1,1,0]
	v_cvt_scalef32_pk_f32_fp4 v[24:25], v25, 1.0 op_sel:[1,1,0]
	v_pk_fma_f32 v[24:25], v[30:31], v[24:25], v[32:33] op_sel_hi:[0,1,1]
	v_cvt_scalef32_pk_f32_fp4 v[32:33], v26, 1.0 op_sel:[1,1,0]
	v_cvt_scalef32_pk_f32_fp4 v[26:27], v27, 1.0 op_sel:[1,1,0]
	v_pk_fma_f32 v[26:27], v[30:31], v[26:27], v[28:29] op_sel_hi:[0,1,1]
	s_waitcnt vmcnt(3)
; #define FP4_AXPY(k) { acc2[k] += w * __builtin_amdgcn_cvt_scalef32_pk_f32_fp4(vr[q].x, 1.0f, k); acc2[4 + k] += w * __builtin_amdgcn_cvt_scalef32_pk_f32_fp4(vr[q].y, 1.0f, k); \
;                       acc2[8 + k] += w * __builtin_amdgcn_cvt_scalef32_pk_f32_fp4(vr[q].z, 1.0f, k); acc2[12 + k] += w * __builtin_amdgcn_cvt_scalef32_pk_f32_fp4(vr[q].w, 1.0f, k); }
; __device__ __forceinline__ void peer_token(const Params& P, int t, int lane, int* sidx, float* sval, const int* sid, const float* sgate, const unsigned* szero) {
;     ...
;         for (int q = 0; q < 8; ++q) {
;             const float w = half ? wq[2 * q + 1] : wq[2 * q];
;     ...
;             FP4_AXPY(0) FP4_AXPY(1) FP4_AXPY(2) FP4_AXPY(3)
;     ...
;         }
	v_cvt_scalef32_pk_f32_fp4 v[28:29], v20, 1.0
	v_pk_fma_f32 v[28:29], v[16:17], v[28:29], v[34:35] op_sel_hi:[0,1,1]
	v_cvt_scalef32_pk_f32_fp4 v[34:35], v22, 1.0
	v_pk_fma_f32 v[50:51], v[30:31], v[50:51], v[64:65] op_sel_hi:[0,1,1]
	v_pk_fma_f32 v[58:59], v[30:31], v[58:59], v[66:67] op_sel_hi:[0,1,1]
	v_pk_fma_f32 v[62:63], v[30:31], v[62:63], v[68:69] op_sel_hi:[0,1,1]
	v_pk_fma_f32 v[32:33], v[30:31], v[32:33], v[36:37] op_sel_hi:[0,1,1]
	v_cvt_scalef32_pk_f32_fp4 v[30:31], v21, 1.0
	v_pk_fma_f32 v[34:35], v[16:17], v[34:35], v[42:43] op_sel_hi:[0,1,1]
	v_cvt_scalef32_pk_f32_fp4 v[42:43], v21, 1.0 op_sel:[1,0,0]
	v_pk_fma_f32 v[30:31], v[16:17], v[30:31], v[38:39] op_sel_hi:[0,1,1]
	v_cvt_scalef32_pk_f32_fp4 v[36:37], v23, 1.0
	v_cvt_scalef32_pk_f32_fp4 v[38:39], v20, 1.0 op_sel:[1,0,0]
	v_pk_fma_f32 v[42:43], v[16:17], v[42:43], v[56:57] op_sel_hi:[0,1,1]
	v_cvt_scalef32_pk_f32_fp4 v[56:57], v22, 1.0 op_sel:[0,1,0]
	v_pk_fma_f32 v[36:37], v[16:17], v[36:37], v[44:45] op_sel_hi:[0,1,1]
	v_pk_fma_f32 v[38:39], v[16:17], v[38:39], v[50:51] op_sel_hi:[0,1,1]
	v_cvt_scalef32_pk_f32_fp4 v[44:45], v22, 1.0 op_sel:[1,0,0]
	v_cvt_scalef32_pk_f32_fp4 v[50:51], v23, 1.0 op_sel:[1,0,0]
	v_pk_fma_f32 v[54:55], v[16:17], v[56:57], v[54:55] op_sel_hi:[0,1,1]
	v_cvt_scalef32_pk_f32_fp4 v[56:57], v23, 1.0 op_sel:[0,1,0]
	v_pk_fma_f32 v[44:45], v[16:17], v[44:45], v[52:53] op_sel_hi:[0,1,1]
	v_pk_fma_f32 v[46:47], v[16:17], v[50:51], v[46:47] op_sel_hi:[0,1,1]
	v_cvt_scalef32_pk_f32_fp4 v[50:51], v20, 1.0 op_sel:[0,1,0]
	v_cvt_scalef32_pk_f32_fp4 v[52:53], v21, 1.0 op_sel:[0,1,0]
	v_pk_fma_f32 v[48:49], v[16:17], v[56:57], v[48:49] op_sel_hi:[0,1,1]
	v_cvt_scalef32_pk_f32_fp4 v[56:57], v20, 1.0 op_sel:[1,1,0]
	v_cvt_scalef32_pk_f32_fp4 v[20:21], v21, 1.0 op_sel:[1,1,0]
	v_pk_fma_f32 v[20:21], v[16:17], v[20:21], v[24:25] op_sel_hi:[0,1,1]
	v_cvt_scalef32_pk_f32_fp4 v[24:25], v22, 1.0 op_sel:[1,1,0]
	v_pk_fma_f32 v[24:25], v[16:17], v[24:25], v[32:33] op_sel_hi:[0,1,1]
	s_waitcnt vmcnt(2)
	v_cvt_scalef32_pk_f32_fp4 v[32:33], v12, 1.0 op_sel:[1,0,0]
	v_pk_fma_f32 v[50:51], v[16:17], v[50:51], v[58:59] op_sel_hi:[0,1,1]
	v_pk_fma_f32 v[58:59], v[18:19], v[32:33], v[38:39] op_sel_hi:[0,1,1]
	v_cvt_scalef32_pk_f32_fp4 v[32:33], v13, 1.0 op_sel:[1,0,0]
	v_pk_fma_f32 v[42:43], v[18:19], v[32:33], v[42:43] op_sel_hi:[0,1,1]
	v_cvt_scalef32_pk_f32_fp4 v[32:33], v14, 1.0 op_sel:[1,0,0]
	v_pk_fma_f32 v[44:45], v[18:19], v[32:33], v[44:45] op_sel_hi:[0,1,1]
	v_cvt_scalef32_pk_f32_fp4 v[32:33], v15, 1.0 op_sel:[1,0,0]
	v_pk_fma_f32 v[46:47], v[18:19], v[32:33], v[46:47] op_sel_hi:[0,1,1]
	v_cvt_scalef32_pk_f32_fp4 v[32:33], v12, 1.0 op_sel:[0,1,0]
	v_pk_fma_f32 v[52:53], v[16:17], v[52:53], v[60:61] op_sel_hi:[0,1,1]
	v_pk_fma_f32 v[50:51], v[18:19], v[32:33], v[50:51] op_sel_hi:[0,1,1]
	v_cvt_scalef32_pk_f32_fp4 v[32:33], v13, 1.0 op_sel:[0,1,0]
	v_pk_fma_f32 v[52:53], v[18:19], v[32:33], v[52:53] op_sel_hi:[0,1,1]
	v_cvt_scalef32_pk_f32_fp4 v[32:33], v14, 1.0 op_sel:[0,1,0]
	v_cvt_scalef32_pk_f32_fp4 v[22:23], v23, 1.0 op_sel:[1,1,0]
	v_pk_fma_f32 v[54:55], v[18:19], v[32:33], v[54:55] op_sel_hi:[0,1,1]
	v_cvt_scalef32_pk_f32_fp4 v[32:33], v15, 1.0 op_sel:[0,1,0]
	v_pk_fma_f32 v[56:57], v[16:17], v[56:57], v[62:63] op_sel_hi:[0,1,1]
	v_pk_fma_f32 v[16:17], v[16:17], v[22:23], v[26:27] op_sel_hi:[0,1,1]
	v_cvt_scalef32_pk_f32_fp4 v[22:23], v12, 1.0
	v_cvt_scalef32_pk_f32_fp4 v[26:27], v13, 1.0
	v_pk_fma_f32 v[48:49], v[18:19], v[32:33], v[48:49] op_sel_hi:[0,1,1]
	v_cvt_scalef32_pk_f32_fp4 v[32:33], v12, 1.0 op_sel:[1,1,0]
	v_cvt_scalef32_pk_f32_fp4 v[12:13], v13, 1.0 op_sel:[1,1,0]
	v_pk_fma_f32 v[22:23], v[18:19], v[22:23], v[28:29] op_sel_hi:[0,1,1]
	v_pk_fma_f32 v[26:27], v[18:19], v[26:27], v[30:31] op_sel_hi:[0,1,1]
	v_cvt_scalef32_pk_f32_fp4 v[28:29], v14, 1.0
	v_cvt_scalef32_pk_f32_fp4 v[30:31], v15, 1.0
	v_pk_fma_f32 v[12:13], v[18:19], v[12:13], v[20:21] op_sel_hi:[0,1,1]
	v_cvt_scalef32_pk_f32_fp4 v[20:21], v14, 1.0 op_sel:[1,1,0]
	v_cvt_scalef32_pk_f32_fp4 v[14:15], v15, 1.0 op_sel:[1,1,0]
	v_pk_fma_f32 v[62:63], v[18:19], v[14:15], v[16:17] op_sel_hi:[0,1,1]
	s_waitcnt vmcnt(1)
	v_cvt_scalef32_pk_f32_fp4 v[14:15], v8, 1.0
	s_waitcnt lgkmcnt(0)
	v_pk_fma_f32 v[38:39], v[4:5], v[14:15], v[22:23] op_sel_hi:[0,1,1]
	v_cvt_scalef32_pk_f32_fp4 v[14:15], v9, 1.0
	v_pk_fma_f32 v[28:29], v[18:19], v[28:29], v[34:35] op_sel_hi:[0,1,1]
	v_pk_fma_f32 v[30:31], v[18:19], v[30:31], v[36:37] op_sel_hi:[0,1,1]
	v_pk_fma_f32 v[36:37], v[4:5], v[14:15], v[26:27] op_sel_hi:[0,1,1]
	v_cvt_scalef32_pk_f32_fp4 v[14:15], v10, 1.0
	v_pk_fma_f32 v[34:35], v[4:5], v[14:15], v[28:29] op_sel_hi:[0,1,1]
	v_cvt_scalef32_pk_f32_fp4 v[14:15], v11, 1.0
	v_pk_fma_f32 v[56:57], v[18:19], v[32:33], v[56:57] op_sel_hi:[0,1,1]
	v_pk_fma_f32 v[32:33], v[4:5], v[14:15], v[30:31] op_sel_hi:[0,1,1]
	v_cvt_scalef32_pk_f32_fp4 v[14:15], v8, 1.0 op_sel:[1,0,0]
	v_pk_fma_f32 v[30:31], v[4:5], v[14:15], v[58:59] op_sel_hi:[0,1,1]
	v_cvt_scalef32_pk_f32_fp4 v[14:15], v9, 1.0 op_sel:[1,0,0]
	v_pk_fma_f32 v[28:29], v[4:5], v[14:15], v[42:43] op_sel_hi:[0,1,1]
	v_cvt_scalef32_pk_f32_fp4 v[14:15], v10, 1.0 op_sel:[1,0,0]
	v_pk_fma_f32 v[26:27], v[4:5], v[14:15], v[44:45] op_sel_hi:[0,1,1]
	v_cvt_scalef32_pk_f32_fp4 v[14:15], v11, 1.0 op_sel:[1,0,0]
	v_pk_fma_f32 v[60:61], v[18:19], v[20:21], v[24:25] op_sel_hi:[0,1,1]
	v_pk_fma_f32 v[24:25], v[4:5], v[14:15], v[46:47] op_sel_hi:[0,1,1]
	v_cvt_scalef32_pk_f32_fp4 v[14:15], v8, 1.0 op_sel:[0,1,0]
	v_pk_fma_f32 v[22:23], v[4:5], v[14:15], v[50:51] op_sel_hi:[0,1,1]
	v_cvt_scalef32_pk_f32_fp4 v[14:15], v9, 1.0 op_sel:[0,1,0]
	v_pk_fma_f32 v[20:21], v[4:5], v[14:15], v[52:53] op_sel_hi:[0,1,1]
	v_cvt_scalef32_pk_f32_fp4 v[14:15], v10, 1.0 op_sel:[0,1,0]
	v_pk_fma_f32 v[18:19], v[4:5], v[14:15], v[54:55] op_sel_hi:[0,1,1]
	v_cvt_scalef32_pk_f32_fp4 v[14:15], v11, 1.0 op_sel:[0,1,0]
	v_pk_fma_f32 v[16:17], v[4:5], v[14:15], v[48:49] op_sel_hi:[0,1,1]
	v_cvt_scalef32_pk_f32_fp4 v[14:15], v8, 1.0 op_sel:[1,1,0]
	v_cvt_scalef32_pk_f32_fp4 v[8:9], v9, 1.0 op_sel:[1,1,0]
	v_pk_fma_f32 v[12:13], v[4:5], v[8:9], v[12:13] op_sel_hi:[0,1,1]
	v_cvt_scalef32_pk_f32_fp4 v[8:9], v10, 1.0 op_sel:[1,1,0]
	v_cvt_scalef32_pk_f32_fp4 v[10:11], v11, 1.0 op_sel:[1,1,0]
	v_pk_fma_f32 v[14:15], v[4:5], v[14:15], v[56:57] op_sel_hi:[0,1,1]
	v_pk_fma_f32 v[8:9], v[4:5], v[8:9], v[60:61] op_sel_hi:[0,1,1]
	v_pk_fma_f32 v[4:5], v[4:5], v[10:11], v[62:63] op_sel_hi:[0,1,1]
	s_waitcnt vmcnt(0)
; #define FP4_AXPY(k) { acc2[k] += w * __builtin_amdgcn_cvt_scalef32_pk_f32_fp4(vr[q].x, 1.0f, k); acc2[4 + k] += w * __builtin_amdgcn_cvt_scalef32_pk_f32_fp4(vr[q].y, 1.0f, k); \
;                       acc2[8 + k] += w * __builtin_amdgcn_cvt_scalef32_pk_f32_fp4(vr[q].z, 1.0f, k); acc2[12 + k] += w * __builtin_amdgcn_cvt_scalef32_pk_f32_fp4(vr[q].w, 1.0f, k); }
; __device__ __forceinline__ void peer_token(const Params& P, int t, int lane, int* sidx, float* sval, const int* sid, const float* sgate, const unsigned* szero) {
;     ...
;         for (int q = 0; q < 8; ++q) {
;             const float w = half ? wq[2 * q + 1] : wq[2 * q];
;     ...
;             FP4_AXPY(0) FP4_AXPY(1) FP4_AXPY(2) FP4_AXPY(3)
;     ...
;         }
	v_cvt_scalef32_pk_f32_fp4 v[10:11], v0, 1.0
	v_pk_fma_f32 v[68:69], v[6:7], v[10:11], v[38:39] op_sel_hi:[0,1,1]
	v_cvt_scalef32_pk_f32_fp4 v[10:11], v1, 1.0
	v_pk_fma_f32 v[58:59], v[6:7], v[10:11], v[36:37] op_sel_hi:[0,1,1]
	v_cvt_scalef32_pk_f32_fp4 v[10:11], v2, 1.0
	v_pk_fma_f32 v[50:51], v[6:7], v[10:11], v[34:35] op_sel_hi:[0,1,1]
	v_cvt_scalef32_pk_f32_fp4 v[10:11], v3, 1.0
	v_pk_fma_f32 v[44:45], v[6:7], v[10:11], v[32:33] op_sel_hi:[0,1,1]
	v_cvt_scalef32_pk_f32_fp4 v[10:11], v0, 1.0 op_sel:[1,0,0]
	v_pk_fma_f32 v[66:67], v[6:7], v[10:11], v[30:31] op_sel_hi:[0,1,1]
	v_cvt_scalef32_pk_f32_fp4 v[10:11], v1, 1.0 op_sel:[1,0,0]
	v_pk_fma_f32 v[60:61], v[6:7], v[10:11], v[28:29] op_sel_hi:[0,1,1]
	v_cvt_scalef32_pk_f32_fp4 v[10:11], v2, 1.0 op_sel:[1,0,0]
	v_pk_fma_f32 v[52:53], v[6:7], v[10:11], v[26:27] op_sel_hi:[0,1,1]
	v_cvt_scalef32_pk_f32_fp4 v[10:11], v3, 1.0 op_sel:[1,0,0]
	v_pk_fma_f32 v[46:47], v[6:7], v[10:11], v[24:25] op_sel_hi:[0,1,1]
	v_cvt_scalef32_pk_f32_fp4 v[10:11], v0, 1.0 op_sel:[0,1,0]
	v_pk_fma_f32 v[70:71], v[6:7], v[10:11], v[22:23] op_sel_hi:[0,1,1]
	v_cvt_scalef32_pk_f32_fp4 v[10:11], v1, 1.0 op_sel:[0,1,0]
	v_pk_fma_f32 v[62:63], v[6:7], v[10:11], v[20:21] op_sel_hi:[0,1,1]
	v_cvt_scalef32_pk_f32_fp4 v[10:11], v2, 1.0 op_sel:[0,1,0]
	v_pk_fma_f32 v[54:55], v[6:7], v[10:11], v[18:19] op_sel_hi:[0,1,1]
	v_cvt_scalef32_pk_f32_fp4 v[10:11], v3, 1.0 op_sel:[0,1,0]
	v_pk_fma_f32 v[48:49], v[6:7], v[10:11], v[16:17] op_sel_hi:[0,1,1]
	v_cvt_scalef32_pk_f32_fp4 v[10:11], v0, 1.0 op_sel:[1,1,0]
	v_cvt_scalef32_pk_f32_fp4 v[0:1], v1, 1.0 op_sel:[1,1,0]
	v_pk_fma_f32 v[64:65], v[6:7], v[0:1], v[12:13] op_sel_hi:[0,1,1]
	v_cvt_scalef32_pk_f32_fp4 v[0:1], v2, 1.0 op_sel:[1,1,0]
	v_pk_fma_f32 v[56:57], v[6:7], v[0:1], v[8:9] op_sel_hi:[0,1,1]
	v_cvt_scalef32_pk_f32_fp4 v[0:1], v3, 1.0 op_sel:[1,1,0]
	v_pk_fma_f32 v[72:73], v[6:7], v[10:11], v[14:15] op_sel_hi:[0,1,1]
	v_pk_fma_f32 v[42:43], v[6:7], v[0:1], v[4:5] op_sel_hi:[0,1,1]
	s_cbranch_scc1 .LBB0_1424
; __device__ __forceinline__ void peer_token(const Params& P, int t, int lane, int* sidx, float* sval, const int* sid, const float* sgate, const unsigned* szero) {
;     ...
;     f32x2 acc[8];
; #pragma unroll
;     for (int j = 0; j < 16; ++j) {
;         const unsigned x0 = __float_as_uint(acc2[j].x), x1 = __float_as_uint(acc2[j].y);
;         const auto r0 = __builtin_amdgcn_permlane32_swap(x0, x0, false, false);
;         const auto r1 = __builtin_amdgcn_permlane32_swap(x1, x1, false, false);
;         acc2[j].x = __uint_as_float(r0[0]) + __uint_as_float(r0[1]);
;         acc2[j].y = __uint_as_float(r1[0]) + __uint_as_float(r1[1]);
;     }
; #pragma unroll
;     for (int j = 0; j < 8; ++j) { acc[j].x = half ? acc2[8 + j].x : acc2[j].x; acc[j].y = half ? acc2[8 + j].y : acc2[j].y; }
;     f32x2 xf[8];
;     {
;         const uint4 xa = *(const uint4*)(xn + lane_o * 16), xb = *(const uint4*)(xn + lane_o * 16 + 8);
;         xf[0] = (f32x2){bflo(xa.x), bfhi(xa.x)}; xf[1] = (f32x2){bflo(xa.y), bfhi(xa.y)}; xf[2] = (f32x2){bflo(xa.z), bfhi(xa.z)}; xf[3] = (f32x2){bflo(xa.w), bfhi(xa.w)};
;         xf[4] = (f32x2){bflo(xb.x), bfhi(xb.x)}; xf[5] = (f32x2){bflo(xb.y), bfhi(xb.y)}; xf[6] = (f32x2){bflo(xb.z), bfhi(xb.z)}; xf[7] = (f32x2){bflo(xb.w), bfhi(xb.w)};
;     }
;     float* o = P.out + (size_t)t * DM + lane_o * 16;
;     float4 h0, h1, h2, h3;
;     {
;         const float4 g0 = *(const float4*)(P.norm_ffn + lane_o * 16), g1 = *(const float4*)(P.norm_ffn + lane_o * 16 + 4), g2 = *(const float4*)(P.norm_ffn + lane_o * 16 + 8), g3 = *(const float4*)(P.norm_ffn + lane_o * 16 + 12);
;         h0.x = xf[0].x * __builtin_amdgcn_rcpf(g0.x) + acc[0].x; h0.y = xf[0].y * __builtin_amdgcn_rcpf(g0.y) + acc[0].y; h0.z = xf[1].x * __builtin_amdgcn_rcpf(g0.z) + acc[1].x; h0.w = xf[1].y * __builtin_amdgcn_rcpf(g0.w) + acc[1].y;
;         h1.x = xf[2].x * __builtin_amdgcn_rcpf(g1.x) + acc[2].x; h1.y = xf[2].y * __builtin_amdgcn_rcpf(g1.y) + acc[2].y; h1.z = xf[3].x * __builtin_amdgcn_rcpf(g1.z) + acc[3].x; h1.w = xf[3].y * __builtin_amdgcn_rcpf(g1.w) + acc[3].y;
;         h2.x = xf[4].x * __builtin_amdgcn_rcpf(g2.x) + acc[4].x; h2.y = xf[4].y * __builtin_amdgcn_rcpf(g2.y) + acc[4].y; h2.z = xf[5].x * __builtin_amdgcn_rcpf(g2.z) + acc[5].x; h2.w = xf[5].y * __builtin_amdgcn_rcpf(g2.w) + acc[5].y;
	v_lshl_add_u64 v[0:1], v[104:105], 1, v[110:111]
	global_load_dwordx4 v[2:5], v[108:109], off
	global_load_dwordx4 v[6:9], v[108:109], off offset:16
	global_load_dwordx4 v[10:13], v[0:1], off
	global_load_dwordx4 v[14:17], v[0:1], off offset:16
	global_load_dwordx4 v[18:21], v[108:109], off offset:32
	global_load_dwordx4 v[22:25], v[108:109], off offset:48
	v_mov_b32_e32 v26, v68
	v_mov_b32_e32 v27, v69
	v_mov_b32_e32 v29, v67
	v_mov_b32_e32 v77, v51
	v_mov_b32_e32 v79, v53
	v_mov_b32_e32 v28, v66
	v_mov_b32_e32 v76, v50
	v_mov_b32_e32 v78, v52
	v_mov_b32_e32 v31, v71
	v_mov_b32_e32 v33, v73
	v_mov_b32_e32 v35, v59
	v_mov_b32_e32 v37, v61
	v_mov_b32_e32 v39, v63
	v_mov_b32_e32 v75, v65
	v_mov_b32_e32 v81, v55
	v_mov_b32_e32 v83, v57
	v_mov_b32_e32 v85, v45
	v_mov_b32_e32 v87, v47
	v_mov_b32_e32 v89, v49
	v_mov_b32_e32 v91, v43
	v_permlane32_swap_b32_e32 v68, v26
	v_permlane32_swap_b32_e32 v69, v27
	v_permlane32_swap_b32_e32 v67, v29
	v_permlane32_swap_b32_e32 v51, v77
	v_permlane32_swap_b32_e32 v53, v79
	v_permlane32_swap_b32_e32 v66, v28
	v_mov_b32_e32 v30, v70
	v_mov_b32_e32 v32, v72
	v_mov_b32_e32 v34, v58
	v_mov_b32_e32 v36, v60
	v_mov_b32_e32 v38, v62
	v_mov_b32_e32 v74, v64
	v_permlane32_swap_b32_e32 v50, v76
	v_permlane32_swap_b32_e32 v52, v78
	v_mov_b32_e32 v80, v54
	v_mov_b32_e32 v82, v56
	v_mov_b32_e32 v84, v44
	v_mov_b32_e32 v86, v46
	v_mov_b32_e32 v88, v48
	v_mov_b32_e32 v90, v42
	v_permlane32_swap_b32_e32 v71, v31
	v_permlane32_swap_b32_e32 v73, v33
	v_permlane32_swap_b32_e32 v59, v35
	v_permlane32_swap_b32_e32 v61, v37
	v_permlane32_swap_b32_e32 v63, v39
	v_permlane32_swap_b32_e32 v65, v75
	v_permlane32_swap_b32_e32 v55, v81
	v_permlane32_swap_b32_e32 v57, v83
	v_permlane32_swap_b32_e32 v45, v85
	v_permlane32_swap_b32_e32 v47, v87
	v_permlane32_swap_b32_e32 v49, v89
	v_permlane32_swap_b32_e32 v43, v91
	v_pk_add_f32 v[26:27], v[68:69], v[26:27]
	v_pk_add_f32 v[28:29], v[66:67], v[28:29]
	v_permlane32_swap_b32_e32 v70, v30
	v_permlane32_swap_b32_e32 v72, v32
	s_waitcnt vmcnt(5)
	v_rcp_f32_e32 v2, v2
	v_rcp_f32_e32 v3, v3
	v_rcp_f32_e32 v4, v4
	v_rcp_f32_e32 v5, v5
	s_waitcnt vmcnt(4)
	v_rcp_f32_e32 v6, v6
	v_rcp_f32_e32 v7, v7
	v_rcp_f32_e32 v8, v8
	v_rcp_f32_e32 v9, v9
	s_waitcnt vmcnt(1)
	v_rcp_f32_e32 v18, v18
	v_rcp_f32_e32 v19, v19
	v_rcp_f32_e32 v20, v20
	v_rcp_f32_e32 v21, v21
	s_waitcnt vmcnt(0)
	v_rcp_f32_e32 v22, v22
	v_rcp_f32_e32 v23, v23
	v_rcp_f32_e32 v24, v24
	v_rcp_f32_e32 v25, v25
	v_permlane32_swap_b32_e32 v58, v34
	v_permlane32_swap_b32_e32 v60, v36
	v_permlane32_swap_b32_e32 v62, v38
	v_permlane32_swap_b32_e32 v64, v74
	v_pk_add_f32 v[50:51], v[50:51], v[76:77]
	v_pk_add_f32 v[52:53], v[52:53], v[78:79]
	v_permlane32_swap_b32_e32 v54, v80
	v_permlane32_swap_b32_e32 v56, v82
	v_permlane32_swap_b32_e32 v44, v84
	v_permlane32_swap_b32_e32 v46, v86
	v_permlane32_swap_b32_e32 v48, v88
	v_permlane32_swap_b32_e32 v42, v90
	v_lshl_add_u64 v[0:1], v[40:41], 2, v[106:107]
	v_lshlrev_b32_e32 v40, 16, v10
	v_and_b32_e32 v41, 0xffff0000, v10
	v_lshlrev_b32_e32 v10, 16, v11
	v_and_b32_e32 v11, 0xffff0000, v11
	v_pk_add_f32 v[30:31], v[70:71], v[30:31]
	v_pk_add_f32 v[32:33], v[72:73], v[32:33]
	v_pk_add_f32 v[34:35], v[58:59], v[34:35]
	v_pk_add_f32 v[36:37], v[60:61], v[36:37]
	v_pk_add_f32 v[38:39], v[62:63], v[38:39]
	v_pk_add_f32 v[58:59], v[64:65], v[74:75]
	v_pk_add_f32 v[54:55], v[54:55], v[80:81]
	v_pk_add_f32 v[56:57], v[56:57], v[82:83]
	v_pk_add_f32 v[44:45], v[44:45], v[84:85]
	v_pk_add_f32 v[46:47], v[46:47], v[86:87]
	v_pk_add_f32 v[48:49], v[48:49], v[88:89]
	v_pk_add_f32 v[42:43], v[42:43], v[90:91]
	v_cndmask_b32_e64 v27, v51, v27, s[0:1]
	v_cndmask_b32_e64 v26, v50, v26, s[0:1]
	v_cndmask_b32_e64 v29, v53, v29, s[0:1]
	v_cndmask_b32_e64 v28, v52, v28, s[0:1]
	v_lshlrev_b32_e32 v92, 16, v12
	v_and_b32_e32 v93, 0xffff0000, v12
	v_lshlrev_b32_e32 v12, 16, v13
	v_and_b32_e32 v13, 0xffff0000, v13
	v_lshlrev_b32_e32 v94, 16, v14
	v_and_b32_e32 v95, 0xffff0000, v14
	v_lshlrev_b32_e32 v14, 16, v15
	v_and_b32_e32 v15, 0xffff0000, v15
	v_lshlrev_b32_e32 v96, 16, v16
	v_and_b32_e32 v97, 0xffff0000, v16
	v_lshlrev_b32_e32 v16, 16, v17
	v_and_b32_e32 v17, 0xffff0000, v17
	v_cndmask_b32_e64 v31, v55, v31, s[0:1]
	v_cndmask_b32_e64 v30, v54, v30, s[0:1]
	v_cndmask_b32_e64 v33, v57, v33, s[0:1]
	v_cndmask_b32_e64 v32, v56, v32, s[0:1]
	v_cndmask_b32_e64 v35, v45, v35, s[0:1]
	v_cndmask_b32_e64 v34, v44, v34, s[0:1]
	v_cndmask_b32_e64 v37, v47, v37, s[0:1]
	v_cndmask_b32_e64 v36, v46, v36, s[0:1]
	v_cndmask_b32_e64 v39, v49, v39, s[0:1]
	v_cndmask_b32_e64 v38, v48, v38, s[0:1]
	v_cndmask_b32_e64 v43, v43, v59, s[0:1]
	v_cndmask_b32_e64 v42, v42, v58, s[0:1]
	v_pk_fma_f32 v[2:3], v[2:3], v[40:41], v[26:27]
	v_pk_fma_f32 v[4:5], v[4:5], v[10:11], v[28:29]
	v_pk_fma_f32 v[6:7], v[6:7], v[92:93], v[30:31]
	v_pk_fma_f32 v[8:9], v[8:9], v[12:13], v[32:33]
	v_pk_fma_f32 v[10:11], v[18:19], v[94:95], v[34:35]
	v_pk_fma_f32 v[12:13], v[20:21], v[14:15], v[36:37]
	v_pk_fma_f32 v[14:15], v[22:23], v[96:97], v[38:39]
	v_pk_fma_f32 v[16:17], v[24:25], v[16:17], v[42:43]
	global_store_dwordx4 v[0:1], v[2:5], off
	global_store_dwordx4 v[0:1], v[6:9], off offset:16
	global_store_dwordx4 v[0:1], v[10:13], off offset:32
	global_store_dwordx4 v[0:1], v[14:17], off offset:48
